# v25 + QKV epilogue rotary lane^32 exchange via v_permlane32_swap on a copy instead of ds_bpermute
# baseline (speedup 1.0000x reference)
; __device__ __forceinline__ u32x4 pack8(f32x4 a, f32x4 b) { u32x4 w; w.x = cvt_pk_bf16(a[0], a[1]); w.y = cvt_pk_bf16(a[2], a[3]); w.z = cvt_pk_bf16(b[0], b[1]); w.w = cvt_pk_bf16(b[2], b[3]); return w; }
; __device__ __forceinline__ bf16x8 pack8(f32x4 a, f32x4 b) { u32x4 w = {cvtpk(a[0], a[1]), cvtpk(a[2], a[3]), cvtpk(b[0], b[1]), cvtpk(b[2], b[3])}; return *reinterpret_cast<bf16x8*>(&w); }
;     PG8_RSTD_HOOKS
;     __device__ __forceinline__ void operator()(const f32x4 (&acc)[2][2][4][2], const Unit& u, int wr, int wc, int fr, int fq, int par) const {
;     ...
;             for (int mm = 0; mm < 2; ++mm) { const int m = 2 * mp + mm;
;                 const int row = row0 + ai * HALF + m * 16; const int s = row & 4095; const float rs = rsv[ai][m];
;                 f32x4 v[2][2];
; #pragma unroll
;                 for (int bj = 0; bj < 2; ++bj)
; #pragma unroll
;                     for (int n = 0; n < 2; ++n) v[bj][n] = acc[ai][bj][m][n] * rs;
;                 if (rot) {
;                     const float sgn = (fq < 2) ? -1.f : 1.f;
; #pragma unroll
;                     for (int n = 0; n < 2; ++n)
; #pragma unroll
;                         for (int j = 0; j < 4; ++j) { const float mine = v[0][n][j]; const float other = __shfl_xor(mine, 32); v[0][n][j] = mine * c[mm][n][j] + sgn * other * sn[mm][n][j]; }
;                 }
; #pragma unroll
;                 for (int bj = 0; bj < 2; ++bj) {
;                     bf16_t* dst = base + ((size_t)((b * 8 + hh) * 4096 + s)) * 128 + cih0 + 32 * bj;
;                     *(u32x4*)dst = pack8(v[bj][0], v[bj][1]);
;                     cs[bj][0] += v[bj][0]; cs[bj][1] += v[bj][1];
;                 }
.LBB0_383:
	v_cndmask_b32_e64 v98, 0, 1, s[0:1]
	s_waitcnt lgkmcnt(0)
	v_pk_mul_f32 v[170:171], v[170:171], v[206:207] op_sel_hi:[1,0]
	v_pk_mul_f32 v[168:169], v[168:169], v[206:207] op_sel_hi:[1,0]
	v_pk_mul_f32 v[166:167], v[166:167], v[206:207] op_sel_hi:[1,0]
	v_cmp_ne_u32_e64 s[42:43], 1, v98
	s_andn2_b64 vcc, exec, s[0:1]
	v_pk_mul_f32 v[164:165], v[164:165], v[206:207] op_sel_hi:[1,0]
	s_cbranch_vccnz .LBB0_385
	v_mov_b32_e32 v98, v169
	s_nop 1
	v_permlane32_swap_b32_e32 v98, v98
	v_mov_b32_e32 v174, v170
	s_nop 1
	v_permlane32_swap_b32_e32 v174, v174
	v_mov_b32_e32 v175, v171
	s_nop 1
	v_permlane32_swap_b32_e32 v175, v175
	v_mov_b32_e32 v172, v168
	s_nop 1
	v_permlane32_swap_b32_e32 v172, v172
	v_mov_b32_e32 v204, v171
	s_waitcnt lgkmcnt(0)
	v_cndmask_b32_e64 v173, v98, -v98, s[36:37]
	v_cndmask_b32_e64 v98, v174, -v174, s[36:37]
	s_waitcnt vmcnt(0)
	v_mul_f32_e32 v174, v130, v98
	v_mov_b32_e32 v98, v165
	s_nop 1
	v_permlane32_swap_b32_e32 v98, v98
	v_cndmask_b32_e64 v197, v175, -v175, s[36:37]
	v_mov_b32_e32 v205, v131
	v_mov_b32_e32 v196, v119
	v_pk_mul_f32 v[168:169], v[168:169], v[116:117]
	v_cndmask_b32_e64 v172, v172, -v172, s[36:37]
	v_pk_mul_f32 v[196:197], v[204:205], v[196:197]
	v_mul_f32_e32 v170, v170, v118
	v_mov_b32_e32 v171, v196
	v_mov_b32_e32 v175, v197
	v_pk_fma_f32 v[168:169], v[128:129], v[172:173], v[168:169]
	s_waitcnt lgkmcnt(0)
	v_cndmask_b32_e64 v173, v98, -v98, s[36:37]
	v_mov_b32_e32 v98, v167
	s_nop 1
	v_permlane32_swap_b32_e32 v98, v98
	v_pk_add_f32 v[170:171], v[170:171], v[174:175]
	v_mov_b32_e32 v174, v166
	s_nop 1
	v_permlane32_swap_b32_e32 v174, v174
	v_mov_b32_e32 v172, v164
	s_nop 1
	v_permlane32_swap_b32_e32 v172, v172
	v_mov_b32_e32 v204, v167
	s_waitcnt lgkmcnt(2)
	v_cndmask_b32_e64 v197, v98, -v98, s[36:37]
	v_mov_b32_e32 v205, v127
	v_mov_b32_e32 v196, v103
	s_waitcnt lgkmcnt(1)
	v_cndmask_b32_e64 v174, v174, -v174, s[36:37]
	v_pk_mul_f32 v[196:197], v[204:205], v[196:197]
	v_pk_mul_f32 v[164:165], v[164:165], v[100:101]
	s_waitcnt lgkmcnt(0)
	v_cndmask_b32_e64 v172, v172, -v172, s[36:37]
	v_mul_f32_e32 v166, v166, v102
	v_mul_f32_e32 v174, v126, v174
	v_mov_b32_e32 v167, v196
	v_mov_b32_e32 v175, v197
	v_pk_fma_f32 v[164:165], v[124:125], v[172:173], v[164:165]
	v_pk_add_f32 v[166:167], v[166:167], v[174:175]
.LBB0_385:
	s_lshl_b32 s1, s3, 1
	s_and_b32 s1, s1, 6
	s_ashr_i32 s0, s2, 4
	s_or_b32 s1, s1, s89
	s_lshl_b32 s3, s0, 15
	s_lshl_b32 s6, s1, 12
	s_or_b32 s3, s6, s3
	v_and_b32_e32 v98, 0xfcf, v198
	v_or_b32_e32 v204, s3, v98
	s_ashr_i32 s91, s90, 31
	v_mov_b32_e32 v172, v206
	v_mov_b32_e32 v173, v206
	s_lshl_b64 s[6:7], s[90:91], 25
	v_ashrrev_i32_e32 v205, 31, v204
	v_mov_b32_e32 v174, v206
	v_mov_b32_e32 v175, v206
	v_pk_mul_f32 v[160:161], v[160:161], v[172:173]
	v_pk_mul_f32 v[156:157], v[156:157], v[172:173]
	v_lshl_add_u64 v[196:197], v[184:185], 0, s[6:7]
	v_lshlrev_b64 v[172:173], 8, v[204:205]
	v_mov_b32_e32 v98, v207
	v_pk_mul_f32 v[162:163], v[162:163], v[174:175]
	v_pk_mul_f32 v[158:159], v[158:159], v[174:175]
	v_lshl_add_u64 v[214:215], v[196:197], 0, v[172:173]
	v_cvt_pk_bf16_f32 v172, v168, v169
	v_cvt_pk_bf16_f32 v173, v170, v171
	v_cvt_pk_bf16_f32 v174, v164, v165
	v_cvt_pk_bf16_f32 v175, v166, v167
	v_pk_mul_f32 v[154:155], v[154:155], v[98:99] op_sel_hi:[1,0]
	v_pk_mul_f32 v[152:153], v[152:153], v[98:99] op_sel_hi:[1,0]
	v_pk_mul_f32 v[150:151], v[150:151], v[98:99] op_sel_hi:[1,0]
	s_and_b64 vcc, exec, s[42:43]
	v_pk_mul_f32 v[148:149], v[148:149], v[98:99] op_sel_hi:[1,0]
	global_store_dwordx4 v[214:215], v[172:175], off sc1
	s_nop 1
	v_cvt_pk_bf16_f32 v172, v160, v161
	v_cvt_pk_bf16_f32 v173, v162, v163
	v_cvt_pk_bf16_f32 v174, v156, v157
	v_cvt_pk_bf16_f32 v175, v158, v159
	global_store_dwordx4 v[214:215], v[172:175], off offset:64 sc1
	s_cbranch_vccnz .LBB0_387
	v_mov_b32_e32 v98, v153
	s_nop 1
	v_permlane32_swap_b32_e32 v98, v98
	v_mov_b32_e32 v174, v154
	s_nop 1
	v_permlane32_swap_b32_e32 v174, v174
	v_mov_b32_e32 v175, v155
	s_nop 1
	v_permlane32_swap_b32_e32 v175, v175
	v_mov_b32_e32 v172, v152
	s_nop 1
	v_permlane32_swap_b32_e32 v172, v172
	v_mov_b32_e32 v216, v155
	s_waitcnt lgkmcnt(0)
	v_cndmask_b32_e64 v173, v98, -v98, s[36:37]
	v_cndmask_b32_e64 v98, v174, -v174, s[36:37]
	s_waitcnt vmcnt(2)
	v_mul_f32_e32 v174, v122, v98
	v_mov_b32_e32 v98, v149
	s_nop 1
	v_permlane32_swap_b32_e32 v98, v98
	v_cndmask_b32_e64 v215, v175, -v175, s[36:37]
	v_mov_b32_e32 v217, v123
	v_mov_b32_e32 v214, v93
	v_pk_mul_f32 v[152:153], v[152:153], v[90:91]
	v_cndmask_b32_e64 v172, v172, -v172, s[36:37]
	v_pk_mul_f32 v[214:215], v[216:217], v[214:215]
	v_mul_f32_e32 v154, v154, v92
	v_mov_b32_e32 v155, v214
	v_mov_b32_e32 v175, v215
	v_pk_fma_f32 v[152:153], v[120:121], v[172:173], v[152:153]
	s_waitcnt lgkmcnt(0)
	v_cndmask_b32_e64 v173, v98, -v98, s[36:37]
	v_mov_b32_e32 v98, v151
	s_nop 1
	v_permlane32_swap_b32_e32 v98, v98
	v_pk_add_f32 v[154:155], v[154:155], v[174:175]
	v_mov_b32_e32 v174, v150
	s_nop 1
	v_permlane32_swap_b32_e32 v174, v174
	v_mov_b32_e32 v172, v148
	s_nop 1
	v_permlane32_swap_b32_e32 v172, v172
	v_mov_b32_e32 v216, v151
	s_waitcnt lgkmcnt(2)
	v_cndmask_b32_e64 v215, v98, -v98, s[36:37]
	v_mov_b32_e32 v217, v97
	v_mov_b32_e32 v214, v85
	s_waitcnt lgkmcnt(1)
	v_cndmask_b32_e64 v174, v174, -v174, s[36:37]
	v_pk_mul_f32 v[214:215], v[216:217], v[214:215]
	v_pk_mul_f32 v[148:149], v[148:149], v[82:83]
	s_waitcnt lgkmcnt(0)
	v_cndmask_b32_e64 v172, v172, -v172, s[36:37]
	v_mul_f32_e32 v150, v150, v84
	v_mul_f32_e32 v174, v96, v174
	v_mov_b32_e32 v151, v214
	v_mov_b32_e32 v175, v215
	v_pk_fma_f32 v[148:149], v[94:95], v[172:173], v[148:149]
	v_pk_add_f32 v[150:151], v[150:151], v[174:175]

; __device__ __forceinline__ u32x4 pack8(f32x4 a, f32x4 b) { u32x4 w; w.x = cvt_pk_bf16(a[0], a[1]); w.y = cvt_pk_bf16(a[2], a[3]); w.z = cvt_pk_bf16(b[0], b[1]); w.w = cvt_pk_bf16(b[2], b[3]); return w; }
; __device__ __forceinline__ bf16x8 pack8(f32x4 a, f32x4 b) { u32x4 w = {cvtpk(a[0], a[1]), cvtpk(a[2], a[3]), cvtpk(b[0], b[1]), cvtpk(b[2], b[3])}; return *reinterpret_cast<bf16x8*>(&w); }
;     PG8_RSTD_HOOKS
;     __device__ __forceinline__ void operator()(const f32x4 (&acc)[2][2][4][2], const Unit& u, int wr, int wc, int fr, int fq, int par) const {
;     ...
;             for (int mm = 0; mm < 2; ++mm) { const int m = 2 * mp + mm;
;                 const int row = row0 + ai * HALF + m * 16; const int s = row & 4095; const float rs = rsv[ai][m];
;                 f32x4 v[2][2];
; #pragma unroll
;                 for (int bj = 0; bj < 2; ++bj)
; #pragma unroll
;                     for (int n = 0; n < 2; ++n) v[bj][n] = acc[ai][bj][m][n] * rs;
;                 if (rot) {
;                     const float sgn = (fq < 2) ? -1.f : 1.f;
; #pragma unroll
;                     for (int n = 0; n < 2; ++n)
; #pragma unroll
;                         for (int j = 0; j < 4; ++j) { const float mine = v[0][n][j]; const float other = __shfl_xor(mine, 32); v[0][n][j] = mine * c[mm][n][j] + sgn * other * sn[mm][n][j]; }
;                 }
; #pragma unroll
;                 for (int bj = 0; bj < 2; ++bj) {
;                     bf16_t* dst = base + ((size_t)((b * 8 + hh) * 4096 + s)) * 128 + cih0 + 32 * bj;
;                     *(u32x4*)dst = pack8(v[bj][0], v[bj][1]);
;                     cs[bj][0] += v[bj][0]; cs[bj][1] += v[bj][1];
;                 }
.LBB0_389:
	v_pk_mul_f32 v[138:139], v[138:139], v[202:203] op_sel_hi:[1,0]
	v_pk_mul_f32 v[136:137], v[136:137], v[202:203] op_sel_hi:[1,0]
	v_pk_mul_f32 v[134:135], v[134:135], v[202:203] op_sel_hi:[1,0]
	s_and_b64 vcc, exec, s[42:43]
	v_pk_mul_f32 v[132:133], v[132:133], v[202:203] op_sel_hi:[1,0]
	s_mov_b32 s91, 0x41000000
	s_cbranch_vccnz .LBB0_391
	v_mov_b32_e32 v98, v137
	s_nop 1
	v_permlane32_swap_b32_e32 v98, v98
	v_mov_b32_e32 v174, v138
	s_nop 1
	v_permlane32_swap_b32_e32 v174, v174
	v_mov_b32_e32 v175, v139
	s_nop 1
	v_permlane32_swap_b32_e32 v175, v175
	v_mov_b32_e32 v172, v136
	s_nop 1
	v_permlane32_swap_b32_e32 v172, v172
	v_mov_b32_e32 v214, v139
	s_waitcnt lgkmcnt(0)
	v_cndmask_b32_e64 v173, v98, -v98, s[36:37]
	v_cndmask_b32_e64 v98, v174, -v174, s[36:37]
	s_waitcnt vmcnt(0)
	v_mul_f32_e32 v174, v130, v98
	v_mov_b32_e32 v98, v133
	s_nop 1
	v_permlane32_swap_b32_e32 v98, v98
	v_cndmask_b32_e64 v207, v175, -v175, s[36:37]
	v_mov_b32_e32 v215, v131
	v_mov_b32_e32 v206, v119
	v_pk_mul_f32 v[136:137], v[136:137], v[116:117]
	v_cndmask_b32_e64 v172, v172, -v172, s[36:37]
	v_pk_mul_f32 v[206:207], v[214:215], v[206:207]
	v_mul_f32_e32 v138, v138, v118
	v_mov_b32_e32 v139, v206
	v_mov_b32_e32 v175, v207
	v_pk_fma_f32 v[136:137], v[128:129], v[172:173], v[136:137]
	s_waitcnt lgkmcnt(0)
	v_cndmask_b32_e64 v173, v98, -v98, s[36:37]
	v_mov_b32_e32 v98, v135
	s_nop 1
	v_permlane32_swap_b32_e32 v98, v98
	v_pk_add_f32 v[138:139], v[138:139], v[174:175]
	v_mov_b32_e32 v174, v134
	s_nop 1
	v_permlane32_swap_b32_e32 v174, v174
	v_mov_b32_e32 v172, v132
	s_nop 1
	v_permlane32_swap_b32_e32 v172, v172
	v_mov_b32_e32 v214, v135
	s_waitcnt lgkmcnt(2)
	v_cndmask_b32_e64 v207, v98, -v98, s[36:37]
	v_mov_b32_e32 v215, v127
	v_mov_b32_e32 v206, v103
	s_waitcnt lgkmcnt(1)
	v_cndmask_b32_e64 v174, v174, -v174, s[36:37]
	v_pk_mul_f32 v[206:207], v[214:215], v[206:207]
	v_pk_mul_f32 v[132:133], v[132:133], v[100:101]
	s_waitcnt lgkmcnt(0)
	v_cndmask_b32_e64 v172, v172, -v172, s[36:37]
	v_mul_f32_e32 v134, v134, v102
	v_mul_f32_e32 v174, v126, v174
	v_mov_b32_e32 v135, v206
	v_mov_b32_e32 v175, v207
	v_pk_fma_f32 v[132:133], v[124:125], v[172:173], v[132:133]
	v_pk_add_f32 v[134:135], v[134:135], v[174:175]
.LBB0_391:
	v_mov_b32_e32 v172, v202
	v_mov_b32_e32 v173, v202
	v_pk_mul_f32 v[112:113], v[112:113], v[172:173]
	v_pk_mul_f32 v[108:109], v[108:109], v[172:173]
	v_or_b32_e32 v172, 32, v204
	v_ashrrev_i32_e32 v173, 31, v172
	v_mov_b32_e32 v174, v202
	v_mov_b32_e32 v175, v202
	v_lshlrev_b64 v[172:173], 8, v[172:173]
	v_mov_b32_e32 v98, v203
	v_pk_mul_f32 v[114:115], v[114:115], v[174:175]
	v_pk_mul_f32 v[110:111], v[110:111], v[174:175]
	v_lshl_add_u64 v[206:207], v[196:197], 0, v[172:173]
	v_cvt_pk_bf16_f32 v172, v136, v137
	v_cvt_pk_bf16_f32 v173, v138, v139
	v_cvt_pk_bf16_f32 v174, v132, v133
	v_cvt_pk_bf16_f32 v175, v134, v135
	v_pk_mul_f32 v[106:107], v[106:107], v[98:99] op_sel_hi:[1,0]
	v_pk_mul_f32 v[104:105], v[104:105], v[98:99] op_sel_hi:[1,0]
	v_pk_mul_f32 v[88:89], v[88:89], v[98:99] op_sel_hi:[1,0]
	s_and_b64 vcc, exec, s[42:43]
	v_pk_mul_f32 v[86:87], v[86:87], v[98:99] op_sel_hi:[1,0]
	global_store_dwordx4 v[206:207], v[172:175], off sc1
	s_nop 1
	v_cvt_pk_bf16_f32 v172, v112, v113
	v_cvt_pk_bf16_f32 v173, v114, v115
	v_cvt_pk_bf16_f32 v174, v108, v109
	v_cvt_pk_bf16_f32 v175, v110, v111
	global_store_dwordx4 v[206:207], v[172:175], off offset:64 sc1
	s_cbranch_vccnz .LBB0_393
	v_mov_b32_e32 v98, v105
	s_nop 1
	v_permlane32_swap_b32_e32 v98, v98
	v_mov_b32_e32 v174, v106
	s_nop 1
	v_permlane32_swap_b32_e32 v174, v174
	v_mov_b32_e32 v175, v107
	s_nop 1
	v_permlane32_swap_b32_e32 v175, v175
	v_mov_b32_e32 v172, v104
	s_nop 1
	v_permlane32_swap_b32_e32 v172, v172
	v_mov_b32_e32 v214, v107
	s_waitcnt lgkmcnt(0)
	v_cndmask_b32_e64 v173, v98, -v98, s[36:37]
	v_cndmask_b32_e64 v98, v174, -v174, s[36:37]
	s_waitcnt vmcnt(2)
	v_mul_f32_e32 v174, v122, v98
	v_mov_b32_e32 v98, v87
	s_nop 1
	v_permlane32_swap_b32_e32 v98, v98
	v_cndmask_b32_e64 v207, v175, -v175, s[36:37]
	v_mov_b32_e32 v215, v123
	v_mov_b32_e32 v206, v93
	v_pk_mul_f32 v[104:105], v[104:105], v[90:91]
	v_cndmask_b32_e64 v172, v172, -v172, s[36:37]
	v_pk_mul_f32 v[206:207], v[214:215], v[206:207]
	v_mul_f32_e32 v106, v106, v92
	v_mov_b32_e32 v107, v206
	v_mov_b32_e32 v175, v207
	v_pk_fma_f32 v[104:105], v[120:121], v[172:173], v[104:105]
	s_waitcnt lgkmcnt(0)
	v_cndmask_b32_e64 v173, v98, -v98, s[36:37]
	v_mov_b32_e32 v98, v89
	s_nop 1
	v_permlane32_swap_b32_e32 v98, v98
	v_pk_add_f32 v[106:107], v[106:107], v[174:175]
	v_mov_b32_e32 v174, v88
	s_nop 1
	v_permlane32_swap_b32_e32 v174, v174
	v_mov_b32_e32 v172, v86
	s_nop 1
	v_permlane32_swap_b32_e32 v172, v172
	v_mov_b32_e32 v214, v89
	s_waitcnt lgkmcnt(2)
	v_cndmask_b32_e64 v207, v98, -v98, s[36:37]
	v_mov_b32_e32 v215, v97
	v_mov_b32_e32 v206, v85
	s_waitcnt lgkmcnt(1)
	v_cndmask_b32_e64 v174, v174, -v174, s[36:37]
	v_pk_mul_f32 v[206:207], v[214:215], v[206:207]
	v_pk_mul_f32 v[86:87], v[86:87], v[82:83]
	s_waitcnt lgkmcnt(0)
	v_cndmask_b32_e64 v172, v172, -v172, s[36:37]
	v_mul_f32_e32 v88, v88, v84
	v_mul_f32_e32 v174, v96, v174
	v_mov_b32_e32 v89, v206
	v_mov_b32_e32 v175, v207
	v_pk_fma_f32 v[86:87], v[94:95], v[172:173], v[86:87]
	v_pk_add_f32 v[88:89], v[88:89], v[174:175]

; __device__ __forceinline__ u32x4 pack8(f32x4 a, f32x4 b) { u32x4 w; w.x = cvt_pk_bf16(a[0], a[1]); w.y = cvt_pk_bf16(a[2], a[3]); w.z = cvt_pk_bf16(b[0], b[1]); w.w = cvt_pk_bf16(b[2], b[3]); return w; }
; __device__ __forceinline__ bf16x8 pack8(f32x4 a, f32x4 b) { u32x4 w = {cvtpk(a[0], a[1]), cvtpk(a[2], a[3]), cvtpk(b[0], b[1]), cvtpk(b[2], b[3])}; return *reinterpret_cast<bf16x8*>(&w); }
;     PG8_RSTD_HOOKS
;     __device__ __forceinline__ void operator()(const f32x4 (&acc)[2][2][4][2], const Unit& u, int wr, int wc, int fr, int fq, int par) const {
;     ...
;             for (int mm = 0; mm < 2; ++mm) { const int m = 2 * mp + mm;
;                 const int row = row0 + ai * HALF + m * 16; const int s = row & 4095; const float rs = rsv[ai][m];
;                 f32x4 v[2][2];
; #pragma unroll
;                 for (int bj = 0; bj < 2; ++bj)
; #pragma unroll
;                     for (int n = 0; n < 2; ++n) v[bj][n] = acc[ai][bj][m][n] * rs;
;                 if (rot) {
;                     const float sgn = (fq < 2) ? -1.f : 1.f;
; #pragma unroll
;                     for (int n = 0; n < 2; ++n)
; #pragma unroll
;                         for (int j = 0; j < 4; ++j) { const float mine = v[0][n][j]; const float other = __shfl_xor(mine, 32); v[0][n][j] = mine * c[mm][n][j] + sgn * other * sn[mm][n][j]; }
;                 }
; #pragma unroll
;                 for (int bj = 0; bj < 2; ++bj) {
;                     bf16_t* dst = base + ((size_t)((b * 8 + hh) * 4096 + s)) * 128 + cih0 + 32 * bj;
;                     *(u32x4*)dst = pack8(v[bj][0], v[bj][1]);
;                     cs[bj][0] += v[bj][0]; cs[bj][1] += v[bj][1];
;                 }
.LBB0_395:
	v_pk_mul_f32 v[72:73], v[72:73], v[200:201] op_sel_hi:[1,0]
	v_pk_mul_f32 v[70:71], v[70:71], v[200:201] op_sel_hi:[1,0]
	v_pk_mul_f32 v[68:69], v[68:69], v[200:201] op_sel_hi:[1,0]
	s_and_b64 vcc, exec, s[42:43]
	v_pk_mul_f32 v[66:67], v[66:67], v[200:201] op_sel_hi:[1,0]
	s_cbranch_vccnz .LBB0_397
	v_mov_b32_e32 v98, v71
	s_nop 1
	v_permlane32_swap_b32_e32 v98, v98
	v_mov_b32_e32 v174, v72
	s_nop 1
	v_permlane32_swap_b32_e32 v174, v174
	v_mov_b32_e32 v175, v73
	s_nop 1
	v_permlane32_swap_b32_e32 v175, v175
	v_mov_b32_e32 v172, v70
	s_nop 1
	v_permlane32_swap_b32_e32 v172, v172
	v_mov_b32_e32 v206, v73
	s_waitcnt lgkmcnt(0)
	v_cndmask_b32_e64 v173, v98, -v98, s[36:37]
	v_cndmask_b32_e64 v98, v174, -v174, s[36:37]
	s_waitcnt vmcnt(0)
	v_mul_f32_e32 v174, v130, v98
	v_mov_b32_e32 v98, v67
	s_nop 1
	v_permlane32_swap_b32_e32 v98, v98
	v_cndmask_b32_e64 v203, v175, -v175, s[36:37]
	v_mov_b32_e32 v207, v131
	v_mov_b32_e32 v202, v119
	v_pk_mul_f32 v[70:71], v[70:71], v[116:117]
	v_cndmask_b32_e64 v172, v172, -v172, s[36:37]
	v_pk_mul_f32 v[202:203], v[206:207], v[202:203]
	v_mul_f32_e32 v72, v72, v118
	v_mov_b32_e32 v73, v202
	v_mov_b32_e32 v175, v203
	v_pk_fma_f32 v[70:71], v[128:129], v[172:173], v[70:71]
	s_waitcnt lgkmcnt(0)
	v_cndmask_b32_e64 v173, v98, -v98, s[36:37]
	v_mov_b32_e32 v98, v69
	s_nop 1
	v_permlane32_swap_b32_e32 v98, v98
	v_pk_add_f32 v[72:73], v[72:73], v[174:175]
	v_mov_b32_e32 v174, v68
	s_nop 1
	v_permlane32_swap_b32_e32 v174, v174
	v_mov_b32_e32 v172, v66
	s_nop 1
	v_permlane32_swap_b32_e32 v172, v172
	v_mov_b32_e32 v206, v69
	s_waitcnt lgkmcnt(2)
	v_cndmask_b32_e64 v203, v98, -v98, s[36:37]
	v_mov_b32_e32 v207, v127
	v_mov_b32_e32 v202, v103
	s_waitcnt lgkmcnt(1)
	v_cndmask_b32_e64 v174, v174, -v174, s[36:37]
	v_pk_mul_f32 v[202:203], v[206:207], v[202:203]
	v_pk_mul_f32 v[66:67], v[66:67], v[100:101]
	s_waitcnt lgkmcnt(0)
	v_cndmask_b32_e64 v172, v172, -v172, s[36:37]
	v_mul_f32_e32 v68, v68, v102
	v_mul_f32_e32 v174, v126, v174
	v_mov_b32_e32 v69, v202
	v_mov_b32_e32 v175, v203
	v_pk_fma_f32 v[66:67], v[124:125], v[172:173], v[66:67]
	v_pk_add_f32 v[68:69], v[68:69], v[174:175]
.LBB0_397:
	v_and_b32_e32 v98, 0xfcf, v204
	v_or_b32_e32 v202, s3, v98
	v_mov_b32_e32 v172, v200
	v_mov_b32_e32 v173, v200
	v_ashrrev_i32_e32 v203, 31, v202
	v_mov_b32_e32 v174, v200
	v_mov_b32_e32 v175, v200
	v_pk_mul_f32 v[62:63], v[62:63], v[172:173]
	v_pk_mul_f32 v[58:59], v[58:59], v[172:173]
	v_lshlrev_b64 v[172:173], 8, v[202:203]
	v_mov_b32_e32 v98, v201
	v_pk_mul_f32 v[64:65], v[64:65], v[174:175]
	v_pk_mul_f32 v[60:61], v[60:61], v[174:175]
	v_lshl_add_u64 v[206:207], v[196:197], 0, v[172:173]
	v_cvt_pk_bf16_f32 v172, v70, v71
	v_cvt_pk_bf16_f32 v173, v72, v73
	v_cvt_pk_bf16_f32 v174, v66, v67
	v_cvt_pk_bf16_f32 v175, v68, v69
	v_pk_mul_f32 v[56:57], v[56:57], v[98:99] op_sel_hi:[1,0]
	v_pk_mul_f32 v[54:55], v[54:55], v[98:99] op_sel_hi:[1,0]
	v_pk_mul_f32 v[52:53], v[52:53], v[98:99] op_sel_hi:[1,0]
	s_and_b64 vcc, exec, s[42:43]
	v_pk_mul_f32 v[50:51], v[50:51], v[98:99] op_sel_hi:[1,0]
	global_store_dwordx4 v[206:207], v[172:175], off sc1
	s_nop 1
	v_cvt_pk_bf16_f32 v172, v62, v63
	v_cvt_pk_bf16_f32 v173, v64, v65
	v_cvt_pk_bf16_f32 v174, v58, v59
	v_cvt_pk_bf16_f32 v175, v60, v61
	global_store_dwordx4 v[206:207], v[172:175], off offset:64 sc1
	s_cbranch_vccnz .LBB0_399
	v_mov_b32_e32 v98, v55
	s_nop 1
	v_permlane32_swap_b32_e32 v98, v98
	v_mov_b32_e32 v174, v56
	s_nop 1
	v_permlane32_swap_b32_e32 v174, v174
	v_mov_b32_e32 v175, v57
	s_nop 1
	v_permlane32_swap_b32_e32 v175, v175
	v_mov_b32_e32 v172, v54
	s_nop 1
	v_permlane32_swap_b32_e32 v172, v172
	v_mov_b32_e32 v214, v57
	s_waitcnt lgkmcnt(0)
	v_cndmask_b32_e64 v173, v98, -v98, s[36:37]
	v_cndmask_b32_e64 v98, v174, -v174, s[36:37]
	s_waitcnt vmcnt(2)
	v_mul_f32_e32 v174, v122, v98
	v_mov_b32_e32 v98, v51
	s_nop 1
	v_permlane32_swap_b32_e32 v98, v98
	v_cndmask_b32_e64 v207, v175, -v175, s[36:37]
	v_mov_b32_e32 v215, v123
	v_mov_b32_e32 v206, v93
	v_pk_mul_f32 v[54:55], v[54:55], v[90:91]
	v_cndmask_b32_e64 v172, v172, -v172, s[36:37]
	v_pk_mul_f32 v[206:207], v[214:215], v[206:207]
	v_mul_f32_e32 v56, v56, v92
	v_mov_b32_e32 v57, v206
	v_mov_b32_e32 v175, v207
	v_pk_fma_f32 v[54:55], v[120:121], v[172:173], v[54:55]
	s_waitcnt lgkmcnt(0)
	v_cndmask_b32_e64 v173, v98, -v98, s[36:37]
	v_mov_b32_e32 v98, v53
	s_nop 1
	v_permlane32_swap_b32_e32 v98, v98
	v_pk_add_f32 v[56:57], v[56:57], v[174:175]
	v_mov_b32_e32 v174, v52
	s_nop 1
	v_permlane32_swap_b32_e32 v174, v174
	v_mov_b32_e32 v172, v50
	s_nop 1
	v_permlane32_swap_b32_e32 v172, v172
	v_mov_b32_e32 v214, v53
	s_waitcnt lgkmcnt(2)
	v_cndmask_b32_e64 v207, v98, -v98, s[36:37]
	v_mov_b32_e32 v215, v97
	v_mov_b32_e32 v206, v85
	s_waitcnt lgkmcnt(1)
	v_cndmask_b32_e64 v174, v174, -v174, s[36:37]
	v_pk_mul_f32 v[206:207], v[214:215], v[206:207]
	v_pk_mul_f32 v[50:51], v[50:51], v[82:83]
	s_waitcnt lgkmcnt(0)
	v_cndmask_b32_e64 v172, v172, -v172, s[36:37]
	v_mul_f32_e32 v52, v52, v84
	v_mul_f32_e32 v174, v96, v174
	v_mov_b32_e32 v53, v206
	v_mov_b32_e32 v175, v207
	v_pk_fma_f32 v[50:51], v[94:95], v[172:173], v[50:51]
	v_pk_add_f32 v[52:53], v[52:53], v[174:175]

; __device__ __forceinline__ u32x4 pack8(f32x4 a, f32x4 b) { u32x4 w; w.x = cvt_pk_bf16(a[0], a[1]); w.y = cvt_pk_bf16(a[2], a[3]); w.z = cvt_pk_bf16(b[0], b[1]); w.w = cvt_pk_bf16(b[2], b[3]); return w; }
; __device__ __forceinline__ bf16x8 pack8(f32x4 a, f32x4 b) { u32x4 w = {cvtpk(a[0], a[1]), cvtpk(a[2], a[3]), cvtpk(b[0], b[1]), cvtpk(b[2], b[3])}; return *reinterpret_cast<bf16x8*>(&w); }
;     PG8_RSTD_HOOKS
;     __device__ __forceinline__ void operator()(const f32x4 (&acc)[2][2][4][2], const Unit& u, int wr, int wc, int fr, int fq, int par) const {
;     ...
;             for (int mm = 0; mm < 2; ++mm) { const int m = 2 * mp + mm;
;                 const int row = row0 + ai * HALF + m * 16; const int s = row & 4095; const float rs = rsv[ai][m];
;                 f32x4 v[2][2];
; #pragma unroll
;                 for (int bj = 0; bj < 2; ++bj)
; #pragma unroll
;                     for (int n = 0; n < 2; ++n) v[bj][n] = acc[ai][bj][m][n] * rs;
;                 if (rot) {
;                     const float sgn = (fq < 2) ? -1.f : 1.f;
; #pragma unroll
;                     for (int n = 0; n < 2; ++n)
; #pragma unroll
;                         for (int j = 0; j < 4; ++j) { const float mine = v[0][n][j]; const float other = __shfl_xor(mine, 32); v[0][n][j] = mine * c[mm][n][j] + sgn * other * sn[mm][n][j]; }
;                 }
; #pragma unroll
;                 for (int bj = 0; bj < 2; ++bj) {
;                     bf16_t* dst = base + ((size_t)((b * 8 + hh) * 4096 + s)) * 128 + cih0 + 32 * bj;
;                     *(u32x4*)dst = pack8(v[bj][0], v[bj][1]);
;                     cs[bj][0] += v[bj][0]; cs[bj][1] += v[bj][1];
;                 }
.LBB0_401:
	v_pk_mul_f32 v[40:41], v[40:41], v[194:195] op_sel_hi:[1,0]
	v_pk_mul_f32 v[38:39], v[38:39], v[194:195] op_sel_hi:[1,0]
	v_pk_mul_f32 v[36:37], v[36:37], v[194:195] op_sel_hi:[1,0]
	s_and_b64 vcc, exec, s[42:43]
	v_pk_mul_f32 v[34:35], v[34:35], v[194:195] op_sel_hi:[1,0]
	s_cbranch_vccnz .LBB0_403
	v_mov_b32_e32 v98, v39
	s_nop 1
	v_permlane32_swap_b32_e32 v98, v98
	v_mov_b32_e32 v173, v40
	s_nop 1
	v_permlane32_swap_b32_e32 v173, v173
	v_mov_b32_e32 v172, v38
	s_nop 1
	v_permlane32_swap_b32_e32 v172, v172
	s_waitcnt vmcnt(0)
	v_pk_mul_f32 v[38:39], v[38:39], v[116:117]
	v_mul_f32_e32 v40, v40, v118
	s_waitcnt lgkmcnt(2)
	v_cndmask_b32_e64 v117, v98, -v98, s[36:37]
	s_waitcnt lgkmcnt(1)
	v_cndmask_b32_e64 v98, v173, -v173, s[36:37]
	v_mul_f32_e32 v118, v130, v98
	v_mov_b32_e32 v98, v35
	s_nop 1
	v_permlane32_swap_b32_e32 v98, v98
	s_waitcnt lgkmcnt(1)
	v_cndmask_b32_e64 v116, v172, -v172, s[36:37]
	v_pk_fma_f32 v[38:39], v[128:129], v[116:117], v[38:39]
	v_mov_b32_e32 v117, v36
	s_nop 1
	v_permlane32_swap_b32_e32 v117, v117
	v_mov_b32_e32 v174, v41
	s_nop 1
	v_permlane32_swap_b32_e32 v174, v174
	v_mov_b32_e32 v116, v34
	s_nop 1
	v_permlane32_swap_b32_e32 v116, v116
	v_pk_mul_f32 v[34:35], v[34:35], v[100:101]
	s_waitcnt lgkmcnt(3)
	v_cndmask_b32_e64 v101, v98, -v98, s[36:37]
	v_mov_b32_e32 v98, v37
	s_nop 1
	v_permlane32_swap_b32_e32 v98, v98
	v_mul_f32_e32 v36, v36, v102
	s_waitcnt lgkmcnt(3)
	v_cndmask_b32_e64 v102, v117, -v117, s[36:37]
	s_waitcnt lgkmcnt(2)
	v_cndmask_b32_e64 v173, v174, -v174, s[36:37]
	v_mov_b32_e32 v130, v41
	v_mov_b32_e32 v172, v119
	s_waitcnt lgkmcnt(1)
	v_cndmask_b32_e64 v100, v116, -v116, s[36:37]
	v_mul_f32_e32 v102, v126, v102
	s_waitcnt lgkmcnt(0)
	v_cndmask_b32_e64 v117, v98, -v98, s[36:37]
	v_mov_b32_e32 v126, v37
	v_mov_b32_e32 v116, v103
	v_pk_mul_f32 v[130:131], v[130:131], v[172:173]
	v_pk_mul_f32 v[116:117], v[126:127], v[116:117]
	v_mov_b32_e32 v41, v130
	v_mov_b32_e32 v119, v131
	v_mov_b32_e32 v37, v116
	v_mov_b32_e32 v103, v117
	v_pk_add_f32 v[40:41], v[40:41], v[118:119]
	v_pk_fma_f32 v[34:35], v[124:125], v[100:101], v[34:35]
	v_pk_add_f32 v[36:37], v[36:37], v[102:103]
.LBB0_403:
	s_waitcnt vmcnt(0)
	v_mov_b32_e32 v100, v194
	v_mov_b32_e32 v101, v194
	v_pk_mul_f32 v[30:31], v[30:31], v[100:101]
	v_pk_mul_f32 v[26:27], v[26:27], v[100:101]
	v_or_b32_e32 v100, 32, v202
	v_ashrrev_i32_e32 v101, 31, v100
	v_lshlrev_b64 v[100:101], 8, v[100:101]
	v_mov_b32_e32 v102, v194
	v_mov_b32_e32 v103, v194
	v_lshl_add_u64 v[116:117], v[196:197], 0, v[100:101]
	v_cvt_pk_bf16_f32 v100, v38, v39
	v_cvt_pk_bf16_f32 v101, v40, v41
	v_pk_mul_f32 v[32:33], v[32:33], v[102:103]
	v_pk_mul_f32 v[28:29], v[28:29], v[102:103]
	v_cvt_pk_bf16_f32 v102, v34, v35
	v_cvt_pk_bf16_f32 v103, v36, v37
	global_store_dwordx4 v[116:117], v[100:103], off sc1
	v_mov_b32_e32 v98, v195
	v_pk_mul_f32 v[24:25], v[24:25], v[98:99] op_sel_hi:[1,0]
	v_cvt_pk_bf16_f32 v100, v30, v31
	v_cvt_pk_bf16_f32 v101, v32, v33
	v_cvt_pk_bf16_f32 v102, v26, v27
	v_cvt_pk_bf16_f32 v103, v28, v29
	global_store_dwordx4 v[116:117], v[100:103], off offset:64 sc1
	v_pk_mul_f32 v[20:21], v[20:21], v[98:99] op_sel_hi:[1,0]
	s_and_b64 vcc, exec, s[42:43]
	v_pk_mul_f32 v[100:101], v[22:23], v[98:99] op_sel_hi:[1,0]
	v_pk_mul_f32 v[22:23], v[18:19], v[98:99] op_sel_hi:[1,0]
	s_cbranch_vccnz .LBB0_405
	v_mov_b32_e32 v102, v100
	s_nop 1
	v_permlane32_swap_b32_e32 v102, v102
	v_pk_mul_f32 v[18:19], v[100:101], v[90:91]
	v_mov_b32_e32 v100, v24
	s_nop 1
	v_permlane32_swap_b32_e32 v100, v100
	v_mov_b32_e32 v98, v101
	s_nop 1
	v_permlane32_swap_b32_e32 v98, v98
	v_mov_b32_e32 v101, v25
	s_nop 1
	v_permlane32_swap_b32_e32 v101, v101
	v_mul_f32_e32 v24, v24, v92
	s_waitcnt lgkmcnt(3)
	v_cndmask_b32_e64 v90, v102, -v102, s[36:37]
	s_waitcnt lgkmcnt(2)
	v_cndmask_b32_e64 v92, v100, -v100, s[36:37]
	v_mul_f32_e32 v92, v122, v92
	s_waitcnt lgkmcnt(0)
	v_cndmask_b32_e64 v101, v101, -v101, s[36:37]
	v_mov_b32_e32 v122, v25
	v_mov_b32_e32 v100, v93
	v_cndmask_b32_e64 v91, v98, -v98, s[36:37]
	v_pk_mul_f32 v[100:101], v[122:123], v[100:101]
	s_nop 0
	v_mov_b32_e32 v25, v100
	v_mov_b32_e32 v93, v101
	v_pk_fma_f32 v[100:101], v[120:121], v[90:91], v[18:19]
	v_pk_mul_f32 v[18:19], v[22:23], v[82:83]
	v_mov_b32_e32 v82, v20
	s_nop 1
	v_permlane32_swap_b32_e32 v82, v82
	v_mov_b32_e32 v90, v23
	s_nop 1
	v_permlane32_swap_b32_e32 v90, v90
	v_mov_b32_e32 v91, v22
	s_nop 1
	v_permlane32_swap_b32_e32 v91, v91
	v_mov_b32_e32 v83, v21
	s_nop 1
	v_permlane32_swap_b32_e32 v83, v83
	v_mul_f32_e32 v20, v20, v84
	s_waitcnt lgkmcnt(3)
	v_cndmask_b32_e64 v82, v82, -v82, s[36:37]
	s_waitcnt lgkmcnt(2)
	v_cndmask_b32_e64 v23, v90, -v90, s[36:37]
	s_waitcnt lgkmcnt(1)
	v_cndmask_b32_e64 v22, v91, -v91, s[36:37]
	v_mul_f32_e32 v82, v96, v82
	s_waitcnt lgkmcnt(0)
	v_cndmask_b32_e64 v91, v83, -v83, s[36:37]
	v_mov_b32_e32 v96, v21
	v_mov_b32_e32 v90, v85
	v_pk_mul_f32 v[84:85], v[96:97], v[90:91]
	v_pk_add_f32 v[24:25], v[24:25], v[92:93]
	v_mov_b32_e32 v21, v84
	v_mov_b32_e32 v83, v85
	v_pk_fma_f32 v[22:23], v[94:95], v[22:23], v[18:19]
	v_pk_add_f32 v[20:21], v[20:21], v[82:83]
